# SSM scan loops rewritten: x kept in registers via v_permlane32_swap (no LDS round trip), recurrence as 4 v_fma per step
# speedup vs baseline: 1.0319x; 1.0279x over previous
.Lssm516_nopf:
	s_nop 9
	v_permlane32_swap_b32_e32 v34, v50
	v_permlane32_swap_b32_e32 v35, v51
	v_permlane32_swap_b32_e32 v36, v52
	v_permlane32_swap_b32_e32 v37, v53
	v_permlane32_swap_b32_e32 v38, v54
	v_permlane32_swap_b32_e32 v39, v55
	v_permlane32_swap_b32_e32 v40, v56
	v_permlane32_swap_b32_e32 v41, v57
	v_permlane32_swap_b32_e32 v42, v58
	v_permlane32_swap_b32_e32 v43, v59
	v_permlane32_swap_b32_e32 v44, v60
	v_permlane32_swap_b32_e32 v45, v61
	v_permlane32_swap_b32_e32 v46, v62
	v_permlane32_swap_b32_e32 v47, v63
	v_permlane32_swap_b32_e32 v48, v64
	v_permlane32_swap_b32_e32 v49, v65
	v_permlane32_swap_b32_e32 v18, v2
	v_permlane32_swap_b32_e32 v19, v3
	v_permlane32_swap_b32_e32 v20, v4
	v_permlane32_swap_b32_e32 v21, v5
	v_permlane32_swap_b32_e32 v22, v6
	v_permlane32_swap_b32_e32 v23, v7
	v_permlane32_swap_b32_e32 v24, v8
	v_permlane32_swap_b32_e32 v25, v9
	v_permlane32_swap_b32_e32 v26, v10
	v_permlane32_swap_b32_e32 v27, v11
	v_permlane32_swap_b32_e32 v28, v12
	v_permlane32_swap_b32_e32 v29, v13
	v_permlane32_swap_b32_e32 v30, v14
	v_permlane32_swap_b32_e32 v31, v15
	v_permlane32_swap_b32_e32 v32, v16
	v_permlane32_swap_b32_e32 v33, v17
	s_nop 1
	v_add_u32_e32 v152, 0x2000, v125
	v_add_u32_e32 v153, 0x2400, v125
	v_add_u32_e32 v154, 0x2800, v125
	v_add_u32_e32 v155, 0x2c00, v125
	v_fma_f32 v146, v116, v122, v34
	v_fma_f32 v147, v116, v123, v18
	v_fma_f32 v142, -v118, v123, v146
	v_fma_f32 v143, v118, v122, v147
	v_cvt_pk_bf16_f32 v148, v142, v143
	v_fma_f32 v146, v116, v142, v35
	v_fma_f32 v147, v116, v143, v19
	v_fma_f32 v144, -v118, v143, v146
	v_fma_f32 v145, v118, v142, v147
	v_cvt_pk_bf16_f32 v149, v144, v145
	ds_write2_b32 v152, v148, v149 offset1:68
	v_fma_f32 v146, v116, v144, v36
	v_fma_f32 v147, v116, v145, v20
	v_fma_f32 v142, -v118, v145, v146
	v_fma_f32 v143, v118, v144, v147
	v_cvt_pk_bf16_f32 v150, v142, v143
	v_fma_f32 v146, v116, v142, v37
	v_fma_f32 v147, v116, v143, v21
	v_fma_f32 v144, -v118, v143, v146
	v_fma_f32 v145, v118, v142, v147
	v_cvt_pk_bf16_f32 v151, v144, v145
	ds_write2_b32 v152, v150, v151 offset0:136 offset1:204
	v_fma_f32 v146, v116, v144, v50
	v_fma_f32 v147, v116, v145, v2
	v_fma_f32 v142, -v118, v145, v146
	v_fma_f32 v143, v118, v144, v147
	v_cvt_pk_bf16_f32 v148, v142, v143
	v_fma_f32 v146, v116, v142, v51
	v_fma_f32 v147, v116, v143, v3
	v_fma_f32 v144, -v118, v143, v146
	v_fma_f32 v145, v118, v142, v147
	v_cvt_pk_bf16_f32 v149, v144, v145
	ds_write2_b32 v153, v148, v149 offset0:16 offset1:84
	v_fma_f32 v146, v116, v144, v52
	v_fma_f32 v147, v116, v145, v4
	v_fma_f32 v142, -v118, v145, v146
	v_fma_f32 v143, v118, v144, v147
	v_cvt_pk_bf16_f32 v150, v142, v143
	v_fma_f32 v146, v116, v142, v53
	v_fma_f32 v147, v116, v143, v5
	v_fma_f32 v144, -v118, v143, v146
	v_fma_f32 v145, v118, v142, v147
	v_cvt_pk_bf16_f32 v151, v144, v145
	ds_write2_b32 v153, v150, v151 offset0:152 offset1:220
	v_fma_f32 v146, v116, v144, v38
	v_fma_f32 v147, v116, v145, v22
	v_fma_f32 v142, -v118, v145, v146
	v_fma_f32 v143, v118, v144, v147
	v_cvt_pk_bf16_f32 v148, v142, v143
	v_fma_f32 v146, v116, v142, v39
	v_fma_f32 v147, v116, v143, v23
	v_fma_f32 v144, -v118, v143, v146
	v_fma_f32 v145, v118, v142, v147
	v_cvt_pk_bf16_f32 v149, v144, v145
	ds_write2_b32 v154, v148, v149 offset0:32 offset1:100
	v_fma_f32 v146, v116, v144, v40
	v_fma_f32 v147, v116, v145, v24
	v_fma_f32 v142, -v118, v145, v146
	v_fma_f32 v143, v118, v144, v147
	v_cvt_pk_bf16_f32 v150, v142, v143
	v_fma_f32 v146, v116, v142, v41
	v_fma_f32 v147, v116, v143, v25
	v_fma_f32 v144, -v118, v143, v146
	v_fma_f32 v145, v118, v142, v147
	v_cvt_pk_bf16_f32 v151, v144, v145
	ds_write2_b32 v154, v150, v151 offset0:168 offset1:236
	v_fma_f32 v146, v116, v144, v54
	v_fma_f32 v147, v116, v145, v6
	v_fma_f32 v142, -v118, v145, v146
	v_fma_f32 v143, v118, v144, v147
	v_cvt_pk_bf16_f32 v148, v142, v143
	v_fma_f32 v146, v116, v142, v55
	v_fma_f32 v147, v116, v143, v7
	v_fma_f32 v144, -v118, v143, v146
	v_fma_f32 v145, v118, v142, v147
	v_cvt_pk_bf16_f32 v149, v144, v145
	ds_write2_b32 v155, v148, v149 offset0:48 offset1:116
	v_fma_f32 v146, v116, v144, v56
	v_fma_f32 v147, v116, v145, v8
	v_fma_f32 v142, -v118, v145, v146
	v_fma_f32 v143, v118, v144, v147
	v_cvt_pk_bf16_f32 v150, v142, v143
	v_fma_f32 v146, v116, v142, v57
	v_fma_f32 v147, v116, v143, v9
	v_fma_f32 v144, -v118, v143, v146
	v_fma_f32 v145, v118, v142, v147
	v_cvt_pk_bf16_f32 v151, v144, v145
	ds_write2_b32 v155, v150, v151 offset0:184 offset1:252
	ds_read_b128 v[22:25], v127 offset:8192
	s_waitcnt lgkmcnt(0)
	v_mfma_f32_16x16x32_bf16 v[18:21], v[84:87], v[22:25], 0
	ds_read_b128 v[22:25], v127 offset:8256
	s_waitcnt lgkmcnt(0)
	v_mfma_f32_16x16x32_bf16 v[18:21], v[88:91], v[22:25], v[18:21]
	ds_read_b128 v[22:25], v127 offset:8320
	s_waitcnt lgkmcnt(0)
	v_mfma_f32_16x16x32_bf16 v[18:21], v[92:95], v[22:25], v[18:21]
	ds_read_b128 v[22:25], v127 offset:8384
	s_waitcnt lgkmcnt(0)
	v_mfma_f32_16x16x32_bf16 v[18:21], v[96:99], v[22:25], v[18:21]
	v_add_u32_e32 v25, s39, v134
	v_add_u32_e32 v24, s39, v133
	v_add_u32_e32 v22, 0xff, v25
	v_cndmask_b32_e64 v22, v22, v24, s[36:37]
	v_ashrrev_i32_e32 v23, 31, v22
	s_nop 2
	v_cvt_pk_bf16_f32 v18, v18, v19
	v_cvt_pk_bf16_f32 v19, v20, v21
	v_lshlrev_b64 v[20:21], 10, v[22:23]
	v_lshl_add_u64 v[20:21], v[114:115], 0, v[20:21]
	global_store_dwordx2 v[20:21], v[18:19], off
	v_subrev_u32_e32 v134, 32, v134
	v_add_u32_e32 v133, 32, v133
	v_fma_f32 v146, v116, v144, v42
	v_fma_f32 v147, v116, v145, v26
	v_fma_f32 v142, -v118, v145, v146
	v_fma_f32 v143, v118, v144, v147
	v_cvt_pk_bf16_f32 v148, v142, v143
	v_fma_f32 v146, v116, v142, v43
	v_fma_f32 v147, v116, v143, v27
	v_fma_f32 v144, -v118, v143, v146
	v_fma_f32 v145, v118, v142, v147
	v_cvt_pk_bf16_f32 v149, v144, v145
	ds_write2_b32 v152, v148, v149 offset1:68
	v_fma_f32 v146, v116, v144, v44
	v_fma_f32 v147, v116, v145, v28
	v_fma_f32 v142, -v118, v145, v146
	v_fma_f32 v143, v118, v144, v147
	v_cvt_pk_bf16_f32 v150, v142, v143
	v_fma_f32 v146, v116, v142, v45
	v_fma_f32 v147, v116, v143, v29
	v_fma_f32 v144, -v118, v143, v146
	v_fma_f32 v145, v118, v142, v147
	v_cvt_pk_bf16_f32 v151, v144, v145
	ds_write2_b32 v152, v150, v151 offset0:136 offset1:204
	v_fma_f32 v146, v116, v144, v58
	v_fma_f32 v147, v116, v145, v10
	v_fma_f32 v142, -v118, v145, v146
	v_fma_f32 v143, v118, v144, v147
	v_cvt_pk_bf16_f32 v148, v142, v143
	v_fma_f32 v146, v116, v142, v59
	v_fma_f32 v147, v116, v143, v11
	v_fma_f32 v144, -v118, v143, v146
	v_fma_f32 v145, v118, v142, v147
	v_cvt_pk_bf16_f32 v149, v144, v145
	ds_write2_b32 v153, v148, v149 offset0:16 offset1:84
	v_fma_f32 v146, v116, v144, v60
	v_fma_f32 v147, v116, v145, v12
	v_fma_f32 v142, -v118, v145, v146
	v_fma_f32 v143, v118, v144, v147
	v_cvt_pk_bf16_f32 v150, v142, v143
	v_fma_f32 v146, v116, v142, v61
	v_fma_f32 v147, v116, v143, v13
	v_fma_f32 v144, -v118, v143, v146
	v_fma_f32 v145, v118, v142, v147
	v_cvt_pk_bf16_f32 v151, v144, v145
	ds_write2_b32 v153, v150, v151 offset0:152 offset1:220
	v_fma_f32 v146, v116, v144, v46
	v_fma_f32 v147, v116, v145, v30
	v_fma_f32 v142, -v118, v145, v146
	v_fma_f32 v143, v118, v144, v147
	v_cvt_pk_bf16_f32 v148, v142, v143
	v_fma_f32 v146, v116, v142, v47
	v_fma_f32 v147, v116, v143, v31
	v_fma_f32 v144, -v118, v143, v146
	v_fma_f32 v145, v118, v142, v147
	v_cvt_pk_bf16_f32 v149, v144, v145
	ds_write2_b32 v154, v148, v149 offset0:32 offset1:100
	v_fma_f32 v146, v116, v144, v48
	v_fma_f32 v147, v116, v145, v32
	v_fma_f32 v142, -v118, v145, v146
	v_fma_f32 v143, v118, v144, v147
	v_cvt_pk_bf16_f32 v150, v142, v143
	v_fma_f32 v146, v116, v142, v49
	v_fma_f32 v147, v116, v143, v33
	v_fma_f32 v144, -v118, v143, v146
	v_fma_f32 v145, v118, v142, v147
	v_cvt_pk_bf16_f32 v151, v144, v145
	ds_write2_b32 v154, v150, v151 offset0:168 offset1:236
	v_fma_f32 v146, v116, v144, v62
	v_fma_f32 v147, v116, v145, v14
	v_fma_f32 v142, -v118, v145, v146
	v_fma_f32 v143, v118, v144, v147
	v_cvt_pk_bf16_f32 v148, v142, v143
	v_fma_f32 v146, v116, v142, v63
	v_fma_f32 v147, v116, v143, v15
	v_fma_f32 v144, -v118, v143, v146
	v_fma_f32 v145, v118, v142, v147
	v_cvt_pk_bf16_f32 v149, v144, v145
	ds_write2_b32 v155, v148, v149 offset0:48 offset1:116
	v_fma_f32 v146, v116, v144, v64
	v_fma_f32 v147, v116, v145, v16
	v_fma_f32 v142, -v118, v145, v146
	v_fma_f32 v143, v118, v144, v147
	v_cvt_pk_bf16_f32 v150, v142, v143
	v_fma_f32 v146, v116, v142, v65
	v_fma_f32 v147, v116, v143, v17
	v_fma_f32 v122, -v118, v143, v146
	v_fma_f32 v123, v118, v142, v147
	v_cvt_pk_bf16_f32 v151, v122, v123
	ds_write2_b32 v155, v150, v151 offset0:184 offset1:252
	ds_read_b128 v[6:9], v127 offset:8192
	s_waitcnt lgkmcnt(0)
	v_mfma_f32_16x16x32_bf16 v[2:5], v[84:87], v[6:9], 0
	ds_read_b128 v[6:9], v127 offset:8256
	s_waitcnt lgkmcnt(0)
	v_mfma_f32_16x16x32_bf16 v[2:5], v[88:91], v[6:9], v[2:5]
	ds_read_b128 v[6:9], v127 offset:8320
	s_waitcnt lgkmcnt(0)
	v_mfma_f32_16x16x32_bf16 v[2:5], v[92:95], v[6:9], v[2:5]
	ds_read_b128 v[6:9], v127 offset:8384
	s_waitcnt lgkmcnt(0)
	v_mfma_f32_16x16x32_bf16 v[2:5], v[96:99], v[6:9], v[2:5]
	v_add_u32_e32 v6, 16, v24
	v_add_u32_e32 v7, 0xef, v25
	v_cndmask_b32_e64 v6, v7, v6, s[36:37]
	v_ashrrev_i32_e32 v7, 31, v6
	s_nop 3
	v_cvt_pk_bf16_f32 v2, v2, v3
	v_cvt_pk_bf16_f32 v3, v4, v5
	v_lshlrev_b64 v[4:5], 10, v[6:7]
	v_lshl_add_u64 v[4:5], v[114:115], 0, v[4:5]
	global_store_dwordx2 v[4:5], v[2:3], off
	s_cbranch_scc0 .LBB0_516
	s_and_b64 vcc, exec, s[44:45]
	s_cbranch_vccz .LBB0_502
	s_ashr_i32 s39, s38, 31
	s_lshl_b64 s[2:3], s[38:39], 3
	s_add_u32 s2, s2, s0
	s_addc_u32 s3, s3, s1
	s_add_u32 s2, s2, s73
	s_addc_u32 s3, s3, s52
	s_lshl_b64 s[2:3], s[2:3], 14
	v_readlane_b32 s6, v251, 21
	v_readlane_b32 s7, v251, 22
	s_add_u32 s2, s6, s2
	v_lshl_or_b32 v2, s53, 9, v108
	s_addc_u32 s3, s7, s3
	global_store_dwordx2 v2, v[122:123], s[2:3]
	s_branch .LBB0_502

.Lssm627_nopf:
	s_nop 9
	v_permlane32_swap_b32_e32 v34, v50
	v_permlane32_swap_b32_e32 v35, v51
	v_permlane32_swap_b32_e32 v36, v52
	v_permlane32_swap_b32_e32 v37, v53
	v_permlane32_swap_b32_e32 v38, v54
	v_permlane32_swap_b32_e32 v39, v55
	v_permlane32_swap_b32_e32 v40, v56
	v_permlane32_swap_b32_e32 v41, v57
	v_permlane32_swap_b32_e32 v42, v58
	v_permlane32_swap_b32_e32 v43, v59
	v_permlane32_swap_b32_e32 v44, v60
	v_permlane32_swap_b32_e32 v45, v61
	v_permlane32_swap_b32_e32 v46, v62
	v_permlane32_swap_b32_e32 v47, v63
	v_permlane32_swap_b32_e32 v48, v64
	v_permlane32_swap_b32_e32 v49, v65
	v_permlane32_swap_b32_e32 v18, v2
	v_permlane32_swap_b32_e32 v19, v3
	v_permlane32_swap_b32_e32 v20, v4
	v_permlane32_swap_b32_e32 v21, v5
	v_permlane32_swap_b32_e32 v22, v6
	v_permlane32_swap_b32_e32 v23, v7
	v_permlane32_swap_b32_e32 v24, v8
	v_permlane32_swap_b32_e32 v25, v9
	v_permlane32_swap_b32_e32 v26, v10
	v_permlane32_swap_b32_e32 v27, v11
	v_permlane32_swap_b32_e32 v28, v12
	v_permlane32_swap_b32_e32 v29, v13
	v_permlane32_swap_b32_e32 v30, v14
	v_permlane32_swap_b32_e32 v31, v15
	v_permlane32_swap_b32_e32 v32, v16
	v_permlane32_swap_b32_e32 v33, v17
	s_nop 1
	v_fma_f32 v146, v82, v106, v34
	v_fma_f32 v147, v82, v107, v18
	v_fma_f32 v142, -v83, v107, v146
	v_fma_f32 v143, v83, v106, v147
	v_fma_f32 v146, v82, v142, v35
	v_fma_f32 v147, v82, v143, v19
	v_fma_f32 v144, -v83, v143, v146
	v_fma_f32 v145, v83, v142, v147
	v_fma_f32 v146, v82, v144, v36
	v_fma_f32 v147, v82, v145, v20
	v_fma_f32 v142, -v83, v145, v146
	v_fma_f32 v143, v83, v144, v147
	v_fma_f32 v146, v82, v142, v37
	v_fma_f32 v147, v82, v143, v21
	v_fma_f32 v144, -v83, v143, v146
	v_fma_f32 v145, v83, v142, v147
	v_fma_f32 v146, v82, v144, v50
	v_fma_f32 v147, v82, v145, v2
	v_fma_f32 v142, -v83, v145, v146
	v_fma_f32 v143, v83, v144, v147
	v_fma_f32 v146, v82, v142, v51
	v_fma_f32 v147, v82, v143, v3
	v_fma_f32 v144, -v83, v143, v146
	v_fma_f32 v145, v83, v142, v147
	v_fma_f32 v146, v82, v144, v52
	v_fma_f32 v147, v82, v145, v4
	v_fma_f32 v142, -v83, v145, v146
	v_fma_f32 v143, v83, v144, v147
	v_fma_f32 v146, v82, v142, v53
	v_fma_f32 v147, v82, v143, v5
	v_fma_f32 v144, -v83, v143, v146
	v_fma_f32 v145, v83, v142, v147
	v_fma_f32 v146, v82, v144, v38
	v_fma_f32 v147, v82, v145, v22
	v_fma_f32 v142, -v83, v145, v146
	v_fma_f32 v143, v83, v144, v147
	v_fma_f32 v146, v82, v142, v39
	v_fma_f32 v147, v82, v143, v23
	v_fma_f32 v144, -v83, v143, v146
	v_fma_f32 v145, v83, v142, v147
	v_fma_f32 v146, v82, v144, v40
	v_fma_f32 v147, v82, v145, v24
	v_fma_f32 v142, -v83, v145, v146
	v_fma_f32 v143, v83, v144, v147
	v_fma_f32 v146, v82, v142, v41
	v_fma_f32 v147, v82, v143, v25
	v_fma_f32 v144, -v83, v143, v146
	v_fma_f32 v145, v83, v142, v147
	v_fma_f32 v146, v82, v144, v54
	v_fma_f32 v147, v82, v145, v6
	v_fma_f32 v142, -v83, v145, v146
	v_fma_f32 v143, v83, v144, v147
	v_fma_f32 v146, v82, v142, v55
	v_fma_f32 v147, v82, v143, v7
	v_fma_f32 v144, -v83, v143, v146
	v_fma_f32 v145, v83, v142, v147
	v_fma_f32 v146, v82, v144, v56
	v_fma_f32 v147, v82, v145, v8
	v_fma_f32 v142, -v83, v145, v146
	v_fma_f32 v143, v83, v144, v147
	v_fma_f32 v146, v82, v142, v57
	v_fma_f32 v147, v82, v143, v9
	v_fma_f32 v144, -v83, v143, v146
	v_fma_f32 v145, v83, v142, v147
	v_fma_f32 v146, v82, v144, v42
	v_fma_f32 v147, v82, v145, v26
	v_fma_f32 v142, -v83, v145, v146
	v_fma_f32 v143, v83, v144, v147
	v_fma_f32 v146, v82, v142, v43
	v_fma_f32 v147, v82, v143, v27
	v_fma_f32 v144, -v83, v143, v146
	v_fma_f32 v145, v83, v142, v147
	v_fma_f32 v146, v82, v144, v44
	v_fma_f32 v147, v82, v145, v28
	v_fma_f32 v142, -v83, v145, v146
	v_fma_f32 v143, v83, v144, v147
	v_fma_f32 v146, v82, v142, v45
	v_fma_f32 v147, v82, v143, v29
	v_fma_f32 v144, -v83, v143, v146
	v_fma_f32 v145, v83, v142, v147
	v_fma_f32 v146, v82, v144, v58
	v_fma_f32 v147, v82, v145, v10
	v_fma_f32 v142, -v83, v145, v146
	v_fma_f32 v143, v83, v144, v147
	v_fma_f32 v146, v82, v142, v59
	v_fma_f32 v147, v82, v143, v11
	v_fma_f32 v144, -v83, v143, v146
	v_fma_f32 v145, v83, v142, v147
	v_fma_f32 v146, v82, v144, v60
	v_fma_f32 v147, v82, v145, v12
	v_fma_f32 v142, -v83, v145, v146
	v_fma_f32 v143, v83, v144, v147
	v_fma_f32 v146, v82, v142, v61
	v_fma_f32 v147, v82, v143, v13
	v_fma_f32 v144, -v83, v143, v146
	v_fma_f32 v145, v83, v142, v147
	v_fma_f32 v146, v82, v144, v46
	v_fma_f32 v147, v82, v145, v30
	v_fma_f32 v142, -v83, v145, v146
	v_fma_f32 v143, v83, v144, v147
	v_fma_f32 v146, v82, v142, v47
	v_fma_f32 v147, v82, v143, v31
	v_fma_f32 v144, -v83, v143, v146
	v_fma_f32 v145, v83, v142, v147
	v_fma_f32 v146, v82, v144, v48
	v_fma_f32 v147, v82, v145, v32
	v_fma_f32 v142, -v83, v145, v146
	v_fma_f32 v143, v83, v144, v147
	v_fma_f32 v146, v82, v142, v49
	v_fma_f32 v147, v82, v143, v33
	v_fma_f32 v144, -v83, v143, v146
	v_fma_f32 v145, v83, v142, v147
	v_fma_f32 v146, v82, v144, v62
	v_fma_f32 v147, v82, v145, v14
	v_fma_f32 v142, -v83, v145, v146
	v_fma_f32 v143, v83, v144, v147
	v_fma_f32 v146, v82, v142, v63
	v_fma_f32 v147, v82, v143, v15
	v_fma_f32 v144, -v83, v143, v146
	v_fma_f32 v145, v83, v142, v147
	v_fma_f32 v146, v82, v144, v64
	v_fma_f32 v147, v82, v145, v16
	v_fma_f32 v142, -v83, v145, v146
	v_fma_f32 v143, v83, v144, v147
	v_fma_f32 v146, v82, v142, v65
	v_fma_f32 v147, v82, v143, v17
	v_fma_f32 v106, -v83, v143, v146
	v_fma_f32 v107, v83, v142, v147
	s_cbranch_scc1 .LBB0_627
	s_lshl_b32 s5, s36, 9
	s_lshl_b32 s6, s37, 8
	s_or_b32 s5, s5, s6
	s_lshl_b32 s3, s3, 3
	s_or_b32 s3, s5, s3
	s_add_i32 s3, s3, s2
	v_lshl_or_b32 v2, s3, 6, v204
	v_mov_b32_e32 v3, v1
	s_mov_b64 s[2:3], 0

.Lssm631_nopf:
	s_nop 9
	v_permlane32_swap_b32_e32 v34, v50
	v_permlane32_swap_b32_e32 v35, v51
	v_permlane32_swap_b32_e32 v36, v52
	v_permlane32_swap_b32_e32 v37, v53
	v_permlane32_swap_b32_e32 v38, v54
	v_permlane32_swap_b32_e32 v39, v55
	v_permlane32_swap_b32_e32 v40, v56
	v_permlane32_swap_b32_e32 v41, v57
	v_permlane32_swap_b32_e32 v42, v58
	v_permlane32_swap_b32_e32 v43, v59
	v_permlane32_swap_b32_e32 v44, v60
	v_permlane32_swap_b32_e32 v45, v61
	v_permlane32_swap_b32_e32 v46, v62
	v_permlane32_swap_b32_e32 v47, v63
	v_permlane32_swap_b32_e32 v48, v64
	v_permlane32_swap_b32_e32 v49, v65
	v_permlane32_swap_b32_e32 v18, v2
	v_permlane32_swap_b32_e32 v19, v3
	v_permlane32_swap_b32_e32 v20, v4
	v_permlane32_swap_b32_e32 v21, v5
	v_permlane32_swap_b32_e32 v22, v6
	v_permlane32_swap_b32_e32 v23, v7
	v_permlane32_swap_b32_e32 v24, v8
	v_permlane32_swap_b32_e32 v25, v9
	v_permlane32_swap_b32_e32 v26, v10
	v_permlane32_swap_b32_e32 v27, v11
	v_permlane32_swap_b32_e32 v28, v12
	v_permlane32_swap_b32_e32 v29, v13
	v_permlane32_swap_b32_e32 v30, v14
	v_permlane32_swap_b32_e32 v31, v15
	v_permlane32_swap_b32_e32 v32, v16
	v_permlane32_swap_b32_e32 v33, v17
	s_nop 1
	v_add_u32_e32 v152, 0x2000, v122
	v_add_u32_e32 v153, 0x2400, v122
	v_add_u32_e32 v154, 0x2800, v122
	v_add_u32_e32 v155, 0x2c00, v122
	v_fma_f32 v146, v114, v106, v34
	v_fma_f32 v147, v114, v107, v18
	v_fma_f32 v142, -v116, v107, v146
	v_fma_f32 v143, v116, v106, v147
	v_cvt_pk_bf16_f32 v148, v142, v143
	v_fma_f32 v146, v114, v142, v35
	v_fma_f32 v147, v114, v143, v19
	v_fma_f32 v144, -v116, v143, v146
	v_fma_f32 v145, v116, v142, v147
	v_cvt_pk_bf16_f32 v149, v144, v145
	ds_write2_b32 v152, v148, v149 offset1:68
	v_fma_f32 v146, v114, v144, v36
	v_fma_f32 v147, v114, v145, v20
	v_fma_f32 v142, -v116, v145, v146
	v_fma_f32 v143, v116, v144, v147
	v_cvt_pk_bf16_f32 v150, v142, v143
	v_fma_f32 v146, v114, v142, v37
	v_fma_f32 v147, v114, v143, v21
	v_fma_f32 v144, -v116, v143, v146
	v_fma_f32 v145, v116, v142, v147
	v_cvt_pk_bf16_f32 v151, v144, v145
	ds_write2_b32 v152, v150, v151 offset0:136 offset1:204
	v_fma_f32 v146, v114, v144, v50
	v_fma_f32 v147, v114, v145, v2
	v_fma_f32 v142, -v116, v145, v146
	v_fma_f32 v143, v116, v144, v147
	v_cvt_pk_bf16_f32 v148, v142, v143
	v_fma_f32 v146, v114, v142, v51
	v_fma_f32 v147, v114, v143, v3
	v_fma_f32 v144, -v116, v143, v146
	v_fma_f32 v145, v116, v142, v147
	v_cvt_pk_bf16_f32 v149, v144, v145
	ds_write2_b32 v153, v148, v149 offset0:16 offset1:84
	v_fma_f32 v146, v114, v144, v52
	v_fma_f32 v147, v114, v145, v4
	v_fma_f32 v142, -v116, v145, v146
	v_fma_f32 v143, v116, v144, v147
	v_cvt_pk_bf16_f32 v150, v142, v143
	v_fma_f32 v146, v114, v142, v53
	v_fma_f32 v147, v114, v143, v5
	v_fma_f32 v144, -v116, v143, v146
	v_fma_f32 v145, v116, v142, v147
	v_cvt_pk_bf16_f32 v151, v144, v145
	ds_write2_b32 v153, v150, v151 offset0:152 offset1:220
	v_fma_f32 v146, v114, v144, v38
	v_fma_f32 v147, v114, v145, v22
	v_fma_f32 v142, -v116, v145, v146
	v_fma_f32 v143, v116, v144, v147
	v_cvt_pk_bf16_f32 v148, v142, v143
	v_fma_f32 v146, v114, v142, v39
	v_fma_f32 v147, v114, v143, v23
	v_fma_f32 v144, -v116, v143, v146
	v_fma_f32 v145, v116, v142, v147
	v_cvt_pk_bf16_f32 v149, v144, v145
	ds_write2_b32 v154, v148, v149 offset0:32 offset1:100
	v_fma_f32 v146, v114, v144, v40
	v_fma_f32 v147, v114, v145, v24
	v_fma_f32 v142, -v116, v145, v146
	v_fma_f32 v143, v116, v144, v147
	v_cvt_pk_bf16_f32 v150, v142, v143
	v_fma_f32 v146, v114, v142, v41
	v_fma_f32 v147, v114, v143, v25
	v_fma_f32 v144, -v116, v143, v146
	v_fma_f32 v145, v116, v142, v147
	v_cvt_pk_bf16_f32 v151, v144, v145
	ds_write2_b32 v154, v150, v151 offset0:168 offset1:236
	v_fma_f32 v146, v114, v144, v54
	v_fma_f32 v147, v114, v145, v6
	v_fma_f32 v142, -v116, v145, v146
	v_fma_f32 v143, v116, v144, v147
	v_cvt_pk_bf16_f32 v148, v142, v143
	v_fma_f32 v146, v114, v142, v55
	v_fma_f32 v147, v114, v143, v7
	v_fma_f32 v144, -v116, v143, v146
	v_fma_f32 v145, v116, v142, v147
	v_cvt_pk_bf16_f32 v149, v144, v145
	ds_write2_b32 v155, v148, v149 offset0:48 offset1:116
	v_fma_f32 v146, v114, v144, v56
	v_fma_f32 v147, v114, v145, v8
	v_fma_f32 v142, -v116, v145, v146
	v_fma_f32 v143, v116, v144, v147
	v_cvt_pk_bf16_f32 v150, v142, v143
	v_fma_f32 v146, v114, v142, v57
	v_fma_f32 v147, v114, v143, v9
	v_fma_f32 v144, -v116, v143, v146
	v_fma_f32 v145, v116, v142, v147
	v_cvt_pk_bf16_f32 v151, v144, v145
	ds_write2_b32 v155, v150, v151 offset0:184 offset1:252
	ds_read_b128 v[22:25], v124 offset:8192
	s_waitcnt lgkmcnt(0)
	v_mfma_f32_16x16x32_bf16 v[18:21], v[82:85], v[22:25], 0
	ds_read_b128 v[22:25], v124 offset:8256
	s_waitcnt lgkmcnt(0)
	v_mfma_f32_16x16x32_bf16 v[18:21], v[86:89], v[22:25], v[18:21]
	ds_read_b128 v[22:25], v124 offset:8320
	s_waitcnt lgkmcnt(0)
	v_mfma_f32_16x16x32_bf16 v[18:21], v[90:93], v[22:25], v[18:21]
	ds_read_b128 v[22:25], v124 offset:8384
	s_waitcnt lgkmcnt(0)
	v_mfma_f32_16x16x32_bf16 v[18:21], v[94:97], v[22:25], v[18:21]
	v_add_u32_e32 v25, s44, v132
	v_add_u32_e32 v24, s44, v131
	v_add_u32_e32 v22, 0xff, v25
	v_cndmask_b32_e32 v22, v22, v24, vcc
	v_ashrrev_i32_e32 v23, 31, v22
	s_nop 2
	v_cvt_pk_bf16_f32 v18, v18, v19
	v_cvt_pk_bf16_f32 v19, v20, v21
	v_lshlrev_b64 v[20:21], 10, v[22:23]
	v_lshl_add_u64 v[20:21], v[112:113], 0, v[20:21]
	global_store_dwordx2 v[20:21], v[18:19], off
	v_subrev_u32_e32 v132, 32, v132
	v_add_u32_e32 v131, 32, v131
	v_fma_f32 v146, v114, v144, v42
	v_fma_f32 v147, v114, v145, v26
	v_fma_f32 v142, -v116, v145, v146
	v_fma_f32 v143, v116, v144, v147
	v_cvt_pk_bf16_f32 v148, v142, v143
	v_fma_f32 v146, v114, v142, v43
	v_fma_f32 v147, v114, v143, v27
	v_fma_f32 v144, -v116, v143, v146
	v_fma_f32 v145, v116, v142, v147
	v_cvt_pk_bf16_f32 v149, v144, v145
	ds_write2_b32 v152, v148, v149 offset1:68
	v_fma_f32 v146, v114, v144, v44
	v_fma_f32 v147, v114, v145, v28
	v_fma_f32 v142, -v116, v145, v146
	v_fma_f32 v143, v116, v144, v147
	v_cvt_pk_bf16_f32 v150, v142, v143
	v_fma_f32 v146, v114, v142, v45
	v_fma_f32 v147, v114, v143, v29
	v_fma_f32 v144, -v116, v143, v146
	v_fma_f32 v145, v116, v142, v147
	v_cvt_pk_bf16_f32 v151, v144, v145
	ds_write2_b32 v152, v150, v151 offset0:136 offset1:204
	v_fma_f32 v146, v114, v144, v58
	v_fma_f32 v147, v114, v145, v10
	v_fma_f32 v142, -v116, v145, v146
	v_fma_f32 v143, v116, v144, v147
	v_cvt_pk_bf16_f32 v148, v142, v143
	v_fma_f32 v146, v114, v142, v59
	v_fma_f32 v147, v114, v143, v11
	v_fma_f32 v144, -v116, v143, v146
	v_fma_f32 v145, v116, v142, v147
	v_cvt_pk_bf16_f32 v149, v144, v145
	ds_write2_b32 v153, v148, v149 offset0:16 offset1:84
	v_fma_f32 v146, v114, v144, v60
	v_fma_f32 v147, v114, v145, v12
	v_fma_f32 v142, -v116, v145, v146
	v_fma_f32 v143, v116, v144, v147
	v_cvt_pk_bf16_f32 v150, v142, v143
	v_fma_f32 v146, v114, v142, v61
	v_fma_f32 v147, v114, v143, v13
	v_fma_f32 v144, -v116, v143, v146
	v_fma_f32 v145, v116, v142, v147
	v_cvt_pk_bf16_f32 v151, v144, v145
	ds_write2_b32 v153, v150, v151 offset0:152 offset1:220
	v_fma_f32 v146, v114, v144, v46
	v_fma_f32 v147, v114, v145, v30
	v_fma_f32 v142, -v116, v145, v146
	v_fma_f32 v143, v116, v144, v147
	v_cvt_pk_bf16_f32 v148, v142, v143
	v_fma_f32 v146, v114, v142, v47
	v_fma_f32 v147, v114, v143, v31
	v_fma_f32 v144, -v116, v143, v146
	v_fma_f32 v145, v116, v142, v147
	v_cvt_pk_bf16_f32 v149, v144, v145
	ds_write2_b32 v154, v148, v149 offset0:32 offset1:100
	v_fma_f32 v146, v114, v144, v48
	v_fma_f32 v147, v114, v145, v32
	v_fma_f32 v142, -v116, v145, v146
	v_fma_f32 v143, v116, v144, v147
	v_cvt_pk_bf16_f32 v150, v142, v143
	v_fma_f32 v146, v114, v142, v49
	v_fma_f32 v147, v114, v143, v33
	v_fma_f32 v144, -v116, v143, v146
	v_fma_f32 v145, v116, v142, v147
	v_cvt_pk_bf16_f32 v151, v144, v145
	ds_write2_b32 v154, v150, v151 offset0:168 offset1:236
	v_fma_f32 v146, v114, v144, v62
	v_fma_f32 v147, v114, v145, v14
	v_fma_f32 v142, -v116, v145, v146
	v_fma_f32 v143, v116, v144, v147
	v_cvt_pk_bf16_f32 v148, v142, v143
	v_fma_f32 v146, v114, v142, v63
	v_fma_f32 v147, v114, v143, v15
	v_fma_f32 v144, -v116, v143, v146
	v_fma_f32 v145, v116, v142, v147
	v_cvt_pk_bf16_f32 v149, v144, v145
	ds_write2_b32 v155, v148, v149 offset0:48 offset1:116
	v_fma_f32 v146, v114, v144, v64
	v_fma_f32 v147, v114, v145, v16
	v_fma_f32 v142, -v116, v145, v146
	v_fma_f32 v143, v116, v144, v147
	v_cvt_pk_bf16_f32 v150, v142, v143
	v_fma_f32 v146, v114, v142, v65
	v_fma_f32 v147, v114, v143, v17
	v_fma_f32 v106, -v116, v143, v146
	v_fma_f32 v107, v116, v142, v147
	v_cvt_pk_bf16_f32 v151, v106, v107
	ds_write2_b32 v155, v150, v151 offset0:184 offset1:252
	ds_read_b128 v[6:9], v124 offset:8192
	s_waitcnt lgkmcnt(0)
	v_mfma_f32_16x16x32_bf16 v[2:5], v[82:85], v[6:9], 0
	ds_read_b128 v[6:9], v124 offset:8256
	s_waitcnt lgkmcnt(0)
	v_mfma_f32_16x16x32_bf16 v[2:5], v[86:89], v[6:9], v[2:5]
	ds_read_b128 v[6:9], v124 offset:8320
	s_waitcnt lgkmcnt(0)
	v_mfma_f32_16x16x32_bf16 v[2:5], v[90:93], v[6:9], v[2:5]
	ds_read_b128 v[6:9], v124 offset:8384
	s_waitcnt lgkmcnt(0)
	v_mfma_f32_16x16x32_bf16 v[2:5], v[94:97], v[6:9], v[2:5]
	v_add_u32_e32 v6, 16, v24
	v_add_u32_e32 v7, 0xef, v25
	v_cndmask_b32_e32 v6, v7, v6, vcc
	v_ashrrev_i32_e32 v7, 31, v6
	s_nop 3
	v_cvt_pk_bf16_f32 v2, v2, v3
	v_cvt_pk_bf16_f32 v3, v4, v5
	v_lshlrev_b64 v[4:5], 10, v[6:7]
	v_lshl_add_u64 v[4:5], v[112:113], 0, v[4:5]
	global_store_dwordx2 v[4:5], v[2:3], off
	s_cbranch_scc1 .LBB0_631
	s_ashr_i32 s37, s36, 31
	s_lshl_b64 s[6:7], s[36:37], 3
	s_add_u32 s5, s6, s0
	s_addc_u32 s7, s7, s1
	s_or_b32 s6, s5, s3
	s_lshl_b64 s[6:7], s[6:7], 11
	s_lshl_b32 s2, s2, 6
	s_or_b32 s2, s6, s2
	v_or_b32_e32 v2, s2, v204
	v_readlane_b32 s2, v251, 21
	v_mov_b32_e32 v3, s7
	v_readlane_b32 s3, v251, 22
	s_branch .LBB0_624
